# cache_convert fast paths (8/4/2 wave-iterations, loads first, fully contiguous 1KB halves per wave instead of 32B lane stride)
# speedup vs baseline: 1.0075x; 1.0064x over previous
; __device__ __forceinline__ void cache_convert(const Params& P, int l, int pct0, int pct1, int part, int nparts) {
;     ...
; #pragma unroll 8
;     for (unsigned gi = g0 + (unsigned)part * 512u + tid; gi < g1; gi += (unsigned)nparts * 512u) {
;         const bool isv = gi >= NGL; const unsigned e = (isv ? gi - NGL : gi) * 8u; const int key = (int)((e >> 9) & 511u);
;         const float* src = (isv ? cv : ck) + e;
;         const f32x4 k0 = *(const f32x4*)src, k1 = *(const f32x4*)(src + 4);
.LBB0_679:
	v_readlane_b32 s16, v10, 63
	s_mul_i32 s17, s13, 7
	s_add_u32 s16, s16, s17
	s_cmp_lt_u32 s16, s12
	s_cbranch_scc0 .Lcc_try4
	v_readlane_b32 s22, v253, 61
	v_readlane_b32 s23, v253, 62
	v_readlane_b32 s24, v253, 63
	v_readlane_b32 s25, v254, 0
	s_mov_b64 s[18:19], s[22:23]
	s_mov_b64 s[20:21], s[24:25]
	s_mov_b32 s0, 0xfffff
	s_mov_b32 s16, 0
	v_and_b32_e32 v2, 63, v208
	v_add_u32_e32 v3, 1, v2
	v_lshrrev_b32_e32 v3, 1, v3
	v_and_b32_e32 v2, 1, v2
	v_sub_u32_e32 v9, v10, v3
	v_lshlrev_b32_e32 v19, 2, v2
	v_mov_b32_e32 v105, 0
	v_mov_b32_e32 v107, 0
	v_mov_b32_e32 v109, 0
	v_mov_b32_e32 v111, 0
	v_mov_b32_e32 v113, 0
	v_mov_b32_e32 v115, 0
	v_mov_b32_e32 v117, 0
	v_mov_b32_e32 v119, 0
	v_mov_b32_e32 v121, 0
	v_mov_b32_e32 v123, 0
	v_mov_b32_e32 v125, 0
	v_mov_b32_e32 v127, 0
	v_mov_b32_e32 v129, 0
	v_mov_b32_e32 v131, 0
	v_mov_b32_e32 v133, 0
	v_mov_b32_e32 v135, 0
	v_add3_u32 v2, v9, s16, 0
	s_nop 0
	v_cmp_lt_u32_e32 vcc, s0, v2
	v_lshl_add_u32 v3, v2, 3, v19
	v_mov_b32_e32 v5, s19
	v_add_u32_e32 v4, 0xff800000, v3
	v_mov_b32_e32 v6, s21
	v_cndmask_b32_e32 v104, v3, v4, vcc
	v_cndmask_b32_e32 v7, v5, v6, vcc
	v_mov_b32_e32 v5, s18
	v_mov_b32_e32 v8, s20
	v_cndmask_b32_e32 v6, v5, v8, vcc
	v_lshl_add_u64 v[6:7], v[6:7], 0, s[62:63]
	v_lshl_add_u64 v[6:7], v[104:105], 2, v[6:7]
	global_load_dwordx4 v[20:23], v[6:7], off
	v_add3_u32 v2, v9, s16, 32
	s_nop 0
	v_cmp_lt_u32_e32 vcc, s0, v2
	v_lshl_add_u32 v3, v2, 3, v19
	v_mov_b32_e32 v5, s19
	v_add_u32_e32 v4, 0xff800000, v3
	v_mov_b32_e32 v6, s21
	v_cndmask_b32_e32 v106, v3, v4, vcc
	v_cndmask_b32_e32 v7, v5, v6, vcc
	v_mov_b32_e32 v5, s18
	v_mov_b32_e32 v8, s20
	v_cndmask_b32_e32 v6, v5, v8, vcc
	v_lshl_add_u64 v[6:7], v[6:7], 0, s[62:63]
	v_lshl_add_u64 v[6:7], v[106:107], 2, v[6:7]
	global_load_dwordx4 v[24:27], v[6:7], off
	s_add_u32 s16, s16, s13
	v_add3_u32 v2, v9, s16, 0
	s_nop 0
	v_cmp_lt_u32_e32 vcc, s0, v2
	v_lshl_add_u32 v3, v2, 3, v19
	v_mov_b32_e32 v5, s19
	v_add_u32_e32 v4, 0xff800000, v3
	v_mov_b32_e32 v6, s21
	v_cndmask_b32_e32 v108, v3, v4, vcc
	v_cndmask_b32_e32 v7, v5, v6, vcc
	v_mov_b32_e32 v5, s18
	v_mov_b32_e32 v8, s20
	v_cndmask_b32_e32 v6, v5, v8, vcc
	v_lshl_add_u64 v[6:7], v[6:7], 0, s[62:63]
	v_lshl_add_u64 v[6:7], v[108:109], 2, v[6:7]
	global_load_dwordx4 v[28:31], v[6:7], off
	v_add3_u32 v2, v9, s16, 32
	s_nop 0
	v_cmp_lt_u32_e32 vcc, s0, v2
	v_lshl_add_u32 v3, v2, 3, v19
	v_mov_b32_e32 v5, s19
	v_add_u32_e32 v4, 0xff800000, v3
	v_mov_b32_e32 v6, s21
	v_cndmask_b32_e32 v110, v3, v4, vcc
	v_cndmask_b32_e32 v7, v5, v6, vcc
	v_mov_b32_e32 v5, s18
	v_mov_b32_e32 v8, s20
	v_cndmask_b32_e32 v6, v5, v8, vcc
	v_lshl_add_u64 v[6:7], v[6:7], 0, s[62:63]
	v_lshl_add_u64 v[6:7], v[110:111], 2, v[6:7]
	global_load_dwordx4 v[32:35], v[6:7], off
	s_add_u32 s16, s16, s13
	v_add3_u32 v2, v9, s16, 0
	s_nop 0
	v_cmp_lt_u32_e32 vcc, s0, v2
	v_lshl_add_u32 v3, v2, 3, v19
	v_mov_b32_e32 v5, s19
	v_add_u32_e32 v4, 0xff800000, v3
	v_mov_b32_e32 v6, s21
	v_cndmask_b32_e32 v112, v3, v4, vcc
	v_cndmask_b32_e32 v7, v5, v6, vcc
	v_mov_b32_e32 v5, s18
	v_mov_b32_e32 v8, s20
	v_cndmask_b32_e32 v6, v5, v8, vcc
	v_lshl_add_u64 v[6:7], v[6:7], 0, s[62:63]
	v_lshl_add_u64 v[6:7], v[112:113], 2, v[6:7]
	global_load_dwordx4 v[36:39], v[6:7], off
	v_add3_u32 v2, v9, s16, 32
	s_nop 0
	v_cmp_lt_u32_e32 vcc, s0, v2
	v_lshl_add_u32 v3, v2, 3, v19
	v_mov_b32_e32 v5, s19
	v_add_u32_e32 v4, 0xff800000, v3
	v_mov_b32_e32 v6, s21
	v_cndmask_b32_e32 v114, v3, v4, vcc
	v_cndmask_b32_e32 v7, v5, v6, vcc
	v_mov_b32_e32 v5, s18
	v_mov_b32_e32 v8, s20
	v_cndmask_b32_e32 v6, v5, v8, vcc
	v_lshl_add_u64 v[6:7], v[6:7], 0, s[62:63]
	v_lshl_add_u64 v[6:7], v[114:115], 2, v[6:7]
	global_load_dwordx4 v[40:43], v[6:7], off
	s_add_u32 s16, s16, s13
	v_add3_u32 v2, v9, s16, 0
	s_nop 0
	v_cmp_lt_u32_e32 vcc, s0, v2
	v_lshl_add_u32 v3, v2, 3, v19
	v_mov_b32_e32 v5, s19
	v_add_u32_e32 v4, 0xff800000, v3
	v_mov_b32_e32 v6, s21
	v_cndmask_b32_e32 v116, v3, v4, vcc
	v_cndmask_b32_e32 v7, v5, v6, vcc
	v_mov_b32_e32 v5, s18
	v_mov_b32_e32 v8, s20
	v_cndmask_b32_e32 v6, v5, v8, vcc
	v_lshl_add_u64 v[6:7], v[6:7], 0, s[62:63]
	v_lshl_add_u64 v[6:7], v[116:117], 2, v[6:7]
	global_load_dwordx4 v[44:47], v[6:7], off
	v_add3_u32 v2, v9, s16, 32
	s_nop 0
	v_cmp_lt_u32_e32 vcc, s0, v2
	v_lshl_add_u32 v3, v2, 3, v19
	v_mov_b32_e32 v5, s19
	v_add_u32_e32 v4, 0xff800000, v3
	v_mov_b32_e32 v6, s21
	v_cndmask_b32_e32 v118, v3, v4, vcc
	v_cndmask_b32_e32 v7, v5, v6, vcc
	v_mov_b32_e32 v5, s18
	v_mov_b32_e32 v8, s20
	v_cndmask_b32_e32 v6, v5, v8, vcc
	v_lshl_add_u64 v[6:7], v[6:7], 0, s[62:63]
	v_lshl_add_u64 v[6:7], v[118:119], 2, v[6:7]
	global_load_dwordx4 v[48:51], v[6:7], off
	s_add_u32 s16, s16, s13
	v_add3_u32 v2, v9, s16, 0
	s_nop 0
	v_cmp_lt_u32_e32 vcc, s0, v2
	v_lshl_add_u32 v3, v2, 3, v19
	v_mov_b32_e32 v5, s19
	v_add_u32_e32 v4, 0xff800000, v3
	v_mov_b32_e32 v6, s21
	v_cndmask_b32_e32 v120, v3, v4, vcc
	v_cndmask_b32_e32 v7, v5, v6, vcc
	v_mov_b32_e32 v5, s18
	v_mov_b32_e32 v8, s20
	v_cndmask_b32_e32 v6, v5, v8, vcc
	v_lshl_add_u64 v[6:7], v[6:7], 0, s[62:63]
	v_lshl_add_u64 v[6:7], v[120:121], 2, v[6:7]
	global_load_dwordx4 v[52:55], v[6:7], off
	v_add3_u32 v2, v9, s16, 32
	s_nop 0
	v_cmp_lt_u32_e32 vcc, s0, v2
	v_lshl_add_u32 v3, v2, 3, v19
	v_mov_b32_e32 v5, s19
	v_add_u32_e32 v4, 0xff800000, v3
	v_mov_b32_e32 v6, s21
	v_cndmask_b32_e32 v122, v3, v4, vcc
	v_cndmask_b32_e32 v7, v5, v6, vcc
	v_mov_b32_e32 v5, s18
	v_mov_b32_e32 v8, s20
	v_cndmask_b32_e32 v6, v5, v8, vcc
	v_lshl_add_u64 v[6:7], v[6:7], 0, s[62:63]
	v_lshl_add_u64 v[6:7], v[122:123], 2, v[6:7]
	global_load_dwordx4 v[56:59], v[6:7], off
	s_add_u32 s16, s16, s13
; __device__ __forceinline__ void cache_convert(const Params& P, int l, int pct0, int pct1, int part, int nparts) {
;     ...
;         const bool isv = gi >= NGL; const unsigned e = (isv ? gi - NGL : gi) * 8u; const int key = (int)((e >> 9) & 511u);
;         const float* src = (isv ? cv : ck) + e;
;         const f32x4 k0 = *(const f32x4*)src, k1 = *(const f32x4*)(src + 4);
;         *(bf16x8*)((isv ? vb : kb) + e) = pack8v(k0, k1);
;         if (key >= 16) { float* d = (isv ? ov : ok) + e - 16 * 512; *(f32x4*)d = k0; *(f32x4*)(d + 4) = k1; }
	v_add3_u32 v2, v9, s16, 0
	s_nop 0
	v_cmp_lt_u32_e32 vcc, s0, v2
	v_lshl_add_u32 v3, v2, 3, v19
	v_mov_b32_e32 v5, s19
	v_add_u32_e32 v4, 0xff800000, v3
	v_mov_b32_e32 v6, s21
	v_cndmask_b32_e32 v124, v3, v4, vcc
	v_cndmask_b32_e32 v7, v5, v6, vcc
	v_mov_b32_e32 v5, s18
	v_mov_b32_e32 v8, s20
	v_cndmask_b32_e32 v6, v5, v8, vcc
	v_lshl_add_u64 v[6:7], v[6:7], 0, s[62:63]
	v_lshl_add_u64 v[6:7], v[124:125], 2, v[6:7]
	global_load_dwordx4 v[60:63], v[6:7], off
	v_add3_u32 v2, v9, s16, 32
	s_nop 0
	v_cmp_lt_u32_e32 vcc, s0, v2
	v_lshl_add_u32 v3, v2, 3, v19
	v_mov_b32_e32 v5, s19
	v_add_u32_e32 v4, 0xff800000, v3
	v_mov_b32_e32 v6, s21
	v_cndmask_b32_e32 v126, v3, v4, vcc
	v_cndmask_b32_e32 v7, v5, v6, vcc
	v_mov_b32_e32 v5, s18
	v_mov_b32_e32 v8, s20
	v_cndmask_b32_e32 v6, v5, v8, vcc
	v_lshl_add_u64 v[6:7], v[6:7], 0, s[62:63]
	v_lshl_add_u64 v[6:7], v[126:127], 2, v[6:7]
	global_load_dwordx4 v[64:67], v[6:7], off
	s_add_u32 s16, s16, s13
	v_add3_u32 v2, v9, s16, 0
	s_nop 0
	v_cmp_lt_u32_e32 vcc, s0, v2
	v_lshl_add_u32 v3, v2, 3, v19
	v_mov_b32_e32 v5, s19
	v_add_u32_e32 v4, 0xff800000, v3
	v_mov_b32_e32 v6, s21
	v_cndmask_b32_e32 v128, v3, v4, vcc
	v_cndmask_b32_e32 v7, v5, v6, vcc
	v_mov_b32_e32 v5, s18
	v_mov_b32_e32 v8, s20
	v_cndmask_b32_e32 v6, v5, v8, vcc
	v_lshl_add_u64 v[6:7], v[6:7], 0, s[62:63]
	v_lshl_add_u64 v[6:7], v[128:129], 2, v[6:7]
	global_load_dwordx4 v[68:71], v[6:7], off
	v_add3_u32 v2, v9, s16, 32
	s_nop 0
	v_cmp_lt_u32_e32 vcc, s0, v2
	v_lshl_add_u32 v3, v2, 3, v19
	v_mov_b32_e32 v5, s19
	v_add_u32_e32 v4, 0xff800000, v3
	v_mov_b32_e32 v6, s21
	v_cndmask_b32_e32 v130, v3, v4, vcc
	v_cndmask_b32_e32 v7, v5, v6, vcc
	v_mov_b32_e32 v5, s18
	v_mov_b32_e32 v8, s20
	v_cndmask_b32_e32 v6, v5, v8, vcc
	v_lshl_add_u64 v[6:7], v[6:7], 0, s[62:63]
	v_lshl_add_u64 v[6:7], v[130:131], 2, v[6:7]
	global_load_dwordx4 v[72:75], v[6:7], off
	s_add_u32 s16, s16, s13
	v_add3_u32 v2, v9, s16, 0
	s_nop 0
	v_cmp_lt_u32_e32 vcc, s0, v2
	v_lshl_add_u32 v3, v2, 3, v19
	v_mov_b32_e32 v5, s19
	v_add_u32_e32 v4, 0xff800000, v3
	v_mov_b32_e32 v6, s21
	v_cndmask_b32_e32 v132, v3, v4, vcc
	v_cndmask_b32_e32 v7, v5, v6, vcc
	v_mov_b32_e32 v5, s18
	v_mov_b32_e32 v8, s20
	v_cndmask_b32_e32 v6, v5, v8, vcc
	v_lshl_add_u64 v[6:7], v[6:7], 0, s[62:63]
	v_lshl_add_u64 v[6:7], v[132:133], 2, v[6:7]
	global_load_dwordx4 v[76:79], v[6:7], off
	v_add3_u32 v2, v9, s16, 32
	s_nop 0
	v_cmp_lt_u32_e32 vcc, s0, v2
	v_lshl_add_u32 v3, v2, 3, v19
	v_mov_b32_e32 v5, s19
	v_add_u32_e32 v4, 0xff800000, v3
	v_mov_b32_e32 v6, s21
	v_cndmask_b32_e32 v134, v3, v4, vcc
	v_cndmask_b32_e32 v7, v5, v6, vcc
	v_mov_b32_e32 v5, s18
	v_mov_b32_e32 v8, s20
	v_cndmask_b32_e32 v6, v5, v8, vcc
	v_lshl_add_u64 v[6:7], v[6:7], 0, s[62:63]
	v_lshl_add_u64 v[6:7], v[134:135], 2, v[6:7]
	global_load_dwordx4 v[80:83], v[6:7], off
	s_mov_b32 s16, 0
	v_add3_u32 v2, v9, s16, 0
	s_mov_b32 s0, 0xfffff
	v_mov_b32_e32 v4, 0x24300000
	v_cmp_lt_u32_e32 vcc, s0, v2
	v_mov_b32_e32 v5, 0x28300000
	v_mov_b32_e32 v17, v1
	v_and_b32_e32 v18, 0x3e000, v104
	v_cndmask_b32_e32 v16, v4, v5, vcc
	v_cmp_ne_u32_e64 s[0:1], 0, v18
	v_lshl_add_u64 v[16:17], s[4:5], 0, v[16:17]
	v_lshl_add_u64 v[16:17], v[104:105], 1, v[16:17]
	s_waitcnt vmcnt(15)
	v_cvt_pk_bf16_f32 v12, v20, v21
	v_cvt_pk_bf16_f32 v13, v22, v23
	s_nop 0
	global_store_dwordx2 v[16:17], v[12:13], off
	s_and_saveexec_b64 s[10:11], s[0:1]
	s_cbranch_execz .Lcc_skip_u8_0
	v_mov_b32_e32 v4, 0x6222000
	v_mov_b32_e32 v5, 0xe222000
	v_cndmask_b32_e32 v4, v4, v5, vcc
	v_mov_b32_e32 v5, v1
	v_lshl_add_u64 v[4:5], s[6:7], 0, v[4:5]
	v_lshl_add_u64 v[4:5], v[104:105], 2, v[4:5]
	v_add_co_u32_e32 v4, vcc, 0xffff8000, v4
	s_nop 1
	v_addc_co_u32_e32 v5, vcc, -1, v5, vcc
	s_nop 0
	global_store_dwordx4 v[4:5], v[20:23], off
.Lcc_skip_u8_0:
	s_or_b64 exec, exec, s[10:11]
	v_add3_u32 v2, v9, s16, 32
	s_mov_b32 s0, 0xfffff
	v_mov_b32_e32 v4, 0x24300000
	v_cmp_lt_u32_e32 vcc, s0, v2
	v_mov_b32_e32 v5, 0x28300000
	v_mov_b32_e32 v17, v1
	v_and_b32_e32 v18, 0x3e000, v106
	v_cndmask_b32_e32 v16, v4, v5, vcc
	v_cmp_ne_u32_e64 s[0:1], 0, v18
	v_lshl_add_u64 v[16:17], s[4:5], 0, v[16:17]
	v_lshl_add_u64 v[16:17], v[106:107], 1, v[16:17]
	s_waitcnt vmcnt(15)
	v_cvt_pk_bf16_f32 v14, v24, v25
	v_cvt_pk_bf16_f32 v15, v26, v27
	s_nop 0
	global_store_dwordx2 v[16:17], v[14:15], off
	s_and_saveexec_b64 s[10:11], s[0:1]
	s_cbranch_execz .Lcc_skip_u8_1
	v_mov_b32_e32 v4, 0x6222000
	v_mov_b32_e32 v5, 0xe222000
	v_cndmask_b32_e32 v4, v4, v5, vcc
	v_mov_b32_e32 v5, v1
	v_lshl_add_u64 v[4:5], s[6:7], 0, v[4:5]
	v_lshl_add_u64 v[4:5], v[106:107], 2, v[4:5]
	v_add_co_u32_e32 v4, vcc, 0xffff8000, v4
	s_nop 1
	v_addc_co_u32_e32 v5, vcc, -1, v5, vcc
	s_nop 0
	global_store_dwordx4 v[4:5], v[24:27], off
.Lcc_skip_u8_1:
	s_or_b64 exec, exec, s[10:11]
	s_add_u32 s16, s16, s13
	v_add3_u32 v2, v9, s16, 0
	s_mov_b32 s0, 0xfffff
	v_mov_b32_e32 v4, 0x24300000
	v_cmp_lt_u32_e32 vcc, s0, v2
	v_mov_b32_e32 v5, 0x28300000
	v_mov_b32_e32 v17, v1
	v_and_b32_e32 v18, 0x3e000, v108
	v_cndmask_b32_e32 v16, v4, v5, vcc
	v_cmp_ne_u32_e64 s[0:1], 0, v18
	v_lshl_add_u64 v[16:17], s[4:5], 0, v[16:17]
	v_lshl_add_u64 v[16:17], v[108:109], 1, v[16:17]
	s_waitcnt vmcnt(15)
	v_cvt_pk_bf16_f32 v100, v28, v29
	v_cvt_pk_bf16_f32 v101, v30, v31
	s_nop 0
	global_store_dwordx2 v[16:17], v[100:101], off
	s_and_saveexec_b64 s[10:11], s[0:1]
	s_cbranch_execz .Lcc_skip_u8_2
	v_mov_b32_e32 v4, 0x6222000
	v_mov_b32_e32 v5, 0xe222000
	v_cndmask_b32_e32 v4, v4, v5, vcc
	v_mov_b32_e32 v5, v1
	v_lshl_add_u64 v[4:5], s[6:7], 0, v[4:5]
	v_lshl_add_u64 v[4:5], v[108:109], 2, v[4:5]
	v_add_co_u32_e32 v4, vcc, 0xffff8000, v4
	s_nop 1
	v_addc_co_u32_e32 v5, vcc, -1, v5, vcc
	s_nop 0
	global_store_dwordx4 v[4:5], v[28:31], off
; __device__ __forceinline__ void cache_convert(const Params& P, int l, int pct0, int pct1, int part, int nparts) {
;     ...
;         const bool isv = gi >= NGL; const unsigned e = (isv ? gi - NGL : gi) * 8u; const int key = (int)((e >> 9) & 511u);
;         const float* src = (isv ? cv : ck) + e;
;         const f32x4 k0 = *(const f32x4*)src, k1 = *(const f32x4*)(src + 4);
;         *(bf16x8*)((isv ? vb : kb) + e) = pack8v(k0, k1);
;         if (key >= 16) { float* d = (isv ? ov : ok) + e - 16 * 512; *(f32x4*)d = k0; *(f32x4*)(d + 4) = k1; }
.Lcc_skip_u8_2:
	s_or_b64 exec, exec, s[10:11]
	v_add3_u32 v2, v9, s16, 32
	s_mov_b32 s0, 0xfffff
	v_mov_b32_e32 v4, 0x24300000
	v_cmp_lt_u32_e32 vcc, s0, v2
	v_mov_b32_e32 v5, 0x28300000
	v_mov_b32_e32 v17, v1
	v_and_b32_e32 v18, 0x3e000, v110
	v_cndmask_b32_e32 v16, v4, v5, vcc
	v_cmp_ne_u32_e64 s[0:1], 0, v18
	v_lshl_add_u64 v[16:17], s[4:5], 0, v[16:17]
	v_lshl_add_u64 v[16:17], v[110:111], 1, v[16:17]
	s_waitcnt vmcnt(15)
	v_cvt_pk_bf16_f32 v102, v32, v33
	v_cvt_pk_bf16_f32 v103, v34, v35
	s_nop 0
	global_store_dwordx2 v[16:17], v[102:103], off
	s_and_saveexec_b64 s[10:11], s[0:1]
	s_cbranch_execz .Lcc_skip_u8_3
	v_mov_b32_e32 v4, 0x6222000
	v_mov_b32_e32 v5, 0xe222000
	v_cndmask_b32_e32 v4, v4, v5, vcc
	v_mov_b32_e32 v5, v1
	v_lshl_add_u64 v[4:5], s[6:7], 0, v[4:5]
	v_lshl_add_u64 v[4:5], v[110:111], 2, v[4:5]
	v_add_co_u32_e32 v4, vcc, 0xffff8000, v4
	s_nop 1
	v_addc_co_u32_e32 v5, vcc, -1, v5, vcc
	s_nop 0
	global_store_dwordx4 v[4:5], v[32:35], off
.Lcc_skip_u8_3:
	s_or_b64 exec, exec, s[10:11]
	s_add_u32 s16, s16, s13
	v_add3_u32 v2, v9, s16, 0
	s_mov_b32 s0, 0xfffff
	v_mov_b32_e32 v4, 0x24300000
	v_cmp_lt_u32_e32 vcc, s0, v2
	v_mov_b32_e32 v5, 0x28300000
	v_mov_b32_e32 v17, v1
	v_and_b32_e32 v18, 0x3e000, v112
	v_cndmask_b32_e32 v16, v4, v5, vcc
	v_cmp_ne_u32_e64 s[0:1], 0, v18
	v_lshl_add_u64 v[16:17], s[4:5], 0, v[16:17]
	v_lshl_add_u64 v[16:17], v[112:113], 1, v[16:17]
	s_waitcnt vmcnt(15)
	v_cvt_pk_bf16_f32 v12, v36, v37
	v_cvt_pk_bf16_f32 v13, v38, v39
	s_nop 0
	global_store_dwordx2 v[16:17], v[12:13], off
	s_and_saveexec_b64 s[10:11], s[0:1]
	s_cbranch_execz .Lcc_skip_u8_4
	v_mov_b32_e32 v4, 0x6222000
	v_mov_b32_e32 v5, 0xe222000
	v_cndmask_b32_e32 v4, v4, v5, vcc
	v_mov_b32_e32 v5, v1
	v_lshl_add_u64 v[4:5], s[6:7], 0, v[4:5]
	v_lshl_add_u64 v[4:5], v[112:113], 2, v[4:5]
	v_add_co_u32_e32 v4, vcc, 0xffff8000, v4
	s_nop 1
	v_addc_co_u32_e32 v5, vcc, -1, v5, vcc
	s_nop 0
	global_store_dwordx4 v[4:5], v[36:39], off
.Lcc_skip_u8_4:
	s_or_b64 exec, exec, s[10:11]
	v_add3_u32 v2, v9, s16, 32
	s_mov_b32 s0, 0xfffff
	v_mov_b32_e32 v4, 0x24300000
	v_cmp_lt_u32_e32 vcc, s0, v2
	v_mov_b32_e32 v5, 0x28300000
	v_mov_b32_e32 v17, v1
	v_and_b32_e32 v18, 0x3e000, v114
	v_cndmask_b32_e32 v16, v4, v5, vcc
	v_cmp_ne_u32_e64 s[0:1], 0, v18
	v_lshl_add_u64 v[16:17], s[4:5], 0, v[16:17]
	v_lshl_add_u64 v[16:17], v[114:115], 1, v[16:17]
	s_waitcnt vmcnt(15)
	v_cvt_pk_bf16_f32 v14, v40, v41
	v_cvt_pk_bf16_f32 v15, v42, v43
	s_nop 0
	global_store_dwordx2 v[16:17], v[14:15], off
	s_and_saveexec_b64 s[10:11], s[0:1]
	s_cbranch_execz .Lcc_skip_u8_5
	v_mov_b32_e32 v4, 0x6222000
	v_mov_b32_e32 v5, 0xe222000
	v_cndmask_b32_e32 v4, v4, v5, vcc
	v_mov_b32_e32 v5, v1
	v_lshl_add_u64 v[4:5], s[6:7], 0, v[4:5]
	v_lshl_add_u64 v[4:5], v[114:115], 2, v[4:5]
	v_add_co_u32_e32 v4, vcc, 0xffff8000, v4
	s_nop 1
	v_addc_co_u32_e32 v5, vcc, -1, v5, vcc
	s_nop 0
	global_store_dwordx4 v[4:5], v[40:43], off
.Lcc_skip_u8_5:
	s_or_b64 exec, exec, s[10:11]
	s_add_u32 s16, s16, s13
	v_add3_u32 v2, v9, s16, 0
	s_mov_b32 s0, 0xfffff
	v_mov_b32_e32 v4, 0x24300000
	v_cmp_lt_u32_e32 vcc, s0, v2
	v_mov_b32_e32 v5, 0x28300000
	v_mov_b32_e32 v17, v1
	v_and_b32_e32 v18, 0x3e000, v116
	v_cndmask_b32_e32 v16, v4, v5, vcc
	v_cmp_ne_u32_e64 s[0:1], 0, v18
	v_lshl_add_u64 v[16:17], s[4:5], 0, v[16:17]
	v_lshl_add_u64 v[16:17], v[116:117], 1, v[16:17]
	s_waitcnt vmcnt(15)
	v_cvt_pk_bf16_f32 v100, v44, v45
	v_cvt_pk_bf16_f32 v101, v46, v47
	s_nop 0
	global_store_dwordx2 v[16:17], v[100:101], off
	s_and_saveexec_b64 s[10:11], s[0:1]
	s_cbranch_execz .Lcc_skip_u8_6
	v_mov_b32_e32 v4, 0x6222000
	v_mov_b32_e32 v5, 0xe222000
	v_cndmask_b32_e32 v4, v4, v5, vcc
	v_mov_b32_e32 v5, v1
	v_lshl_add_u64 v[4:5], s[6:7], 0, v[4:5]
	v_lshl_add_u64 v[4:5], v[116:117], 2, v[4:5]
	v_add_co_u32_e32 v4, vcc, 0xffff8000, v4
	s_nop 1
	v_addc_co_u32_e32 v5, vcc, -1, v5, vcc
	s_nop 0
	global_store_dwordx4 v[4:5], v[44:47], off
.Lcc_skip_u8_6:
	s_or_b64 exec, exec, s[10:11]
	v_add3_u32 v2, v9, s16, 32
	s_mov_b32 s0, 0xfffff
	v_mov_b32_e32 v4, 0x24300000
	v_cmp_lt_u32_e32 vcc, s0, v2
	v_mov_b32_e32 v5, 0x28300000
	v_mov_b32_e32 v17, v1
	v_and_b32_e32 v18, 0x3e000, v118
	v_cndmask_b32_e32 v16, v4, v5, vcc
	v_cmp_ne_u32_e64 s[0:1], 0, v18
	v_lshl_add_u64 v[16:17], s[4:5], 0, v[16:17]
	v_lshl_add_u64 v[16:17], v[118:119], 1, v[16:17]
	s_waitcnt vmcnt(15)
	v_cvt_pk_bf16_f32 v102, v48, v49
	v_cvt_pk_bf16_f32 v103, v50, v51
	s_nop 0
	global_store_dwordx2 v[16:17], v[102:103], off
	s_and_saveexec_b64 s[10:11], s[0:1]
	s_cbranch_execz .Lcc_skip_u8_7
	v_mov_b32_e32 v4, 0x6222000
	v_mov_b32_e32 v5, 0xe222000
	v_cndmask_b32_e32 v4, v4, v5, vcc
	v_mov_b32_e32 v5, v1
	v_lshl_add_u64 v[4:5], s[6:7], 0, v[4:5]
	v_lshl_add_u64 v[4:5], v[118:119], 2, v[4:5]
	v_add_co_u32_e32 v4, vcc, 0xffff8000, v4
	s_nop 1
	v_addc_co_u32_e32 v5, vcc, -1, v5, vcc
	s_nop 0
	global_store_dwordx4 v[4:5], v[48:51], off
.Lcc_skip_u8_7:
	s_or_b64 exec, exec, s[10:11]
	s_add_u32 s16, s16, s13
	v_add3_u32 v2, v9, s16, 0
	s_mov_b32 s0, 0xfffff
	v_mov_b32_e32 v4, 0x24300000
	v_cmp_lt_u32_e32 vcc, s0, v2
	v_mov_b32_e32 v5, 0x28300000
	v_mov_b32_e32 v17, v1
	v_and_b32_e32 v18, 0x3e000, v120
	v_cndmask_b32_e32 v16, v4, v5, vcc
	v_cmp_ne_u32_e64 s[0:1], 0, v18
	v_lshl_add_u64 v[16:17], s[4:5], 0, v[16:17]
	v_lshl_add_u64 v[16:17], v[120:121], 1, v[16:17]
	s_waitcnt vmcnt(15)
	v_cvt_pk_bf16_f32 v12, v52, v53
	v_cvt_pk_bf16_f32 v13, v54, v55
	s_nop 0
	global_store_dwordx2 v[16:17], v[12:13], off
	s_and_saveexec_b64 s[10:11], s[0:1]
	s_cbranch_execz .Lcc_skip_u8_8
	v_mov_b32_e32 v4, 0x6222000
	v_mov_b32_e32 v5, 0xe222000
	v_cndmask_b32_e32 v4, v4, v5, vcc
	v_mov_b32_e32 v5, v1
	v_lshl_add_u64 v[4:5], s[6:7], 0, v[4:5]
	v_lshl_add_u64 v[4:5], v[120:121], 2, v[4:5]
	v_add_co_u32_e32 v4, vcc, 0xffff8000, v4
	s_nop 1
	v_addc_co_u32_e32 v5, vcc, -1, v5, vcc
	s_nop 0
	global_store_dwordx4 v[4:5], v[52:55], off
; __device__ __forceinline__ void cache_convert(const Params& P, int l, int pct0, int pct1, int part, int nparts) {
;     ...
;         const bool isv = gi >= NGL; const unsigned e = (isv ? gi - NGL : gi) * 8u; const int key = (int)((e >> 9) & 511u);
;         const float* src = (isv ? cv : ck) + e;
;         const f32x4 k0 = *(const f32x4*)src, k1 = *(const f32x4*)(src + 4);
;         *(bf16x8*)((isv ? vb : kb) + e) = pack8v(k0, k1);
;         if (key >= 16) { float* d = (isv ? ov : ok) + e - 16 * 512; *(f32x4*)d = k0; *(f32x4*)(d + 4) = k1; }
.Lcc_skip_u8_8:
	s_or_b64 exec, exec, s[10:11]
	v_add3_u32 v2, v9, s16, 32
	s_mov_b32 s0, 0xfffff
	v_mov_b32_e32 v4, 0x24300000
	v_cmp_lt_u32_e32 vcc, s0, v2
	v_mov_b32_e32 v5, 0x28300000
	v_mov_b32_e32 v17, v1
	v_and_b32_e32 v18, 0x3e000, v122
	v_cndmask_b32_e32 v16, v4, v5, vcc
	v_cmp_ne_u32_e64 s[0:1], 0, v18
	v_lshl_add_u64 v[16:17], s[4:5], 0, v[16:17]
	v_lshl_add_u64 v[16:17], v[122:123], 1, v[16:17]
	s_waitcnt vmcnt(15)
	v_cvt_pk_bf16_f32 v14, v56, v57
	v_cvt_pk_bf16_f32 v15, v58, v59
	s_nop 0
	global_store_dwordx2 v[16:17], v[14:15], off
	s_and_saveexec_b64 s[10:11], s[0:1]
	s_cbranch_execz .Lcc_skip_u8_9
	v_mov_b32_e32 v4, 0x6222000
	v_mov_b32_e32 v5, 0xe222000
	v_cndmask_b32_e32 v4, v4, v5, vcc
	v_mov_b32_e32 v5, v1
	v_lshl_add_u64 v[4:5], s[6:7], 0, v[4:5]
	v_lshl_add_u64 v[4:5], v[122:123], 2, v[4:5]
	v_add_co_u32_e32 v4, vcc, 0xffff8000, v4
	s_nop 1
	v_addc_co_u32_e32 v5, vcc, -1, v5, vcc
	s_nop 0
	global_store_dwordx4 v[4:5], v[56:59], off
.Lcc_skip_u8_9:
	s_or_b64 exec, exec, s[10:11]
	s_add_u32 s16, s16, s13
	v_add3_u32 v2, v9, s16, 0
	s_mov_b32 s0, 0xfffff
	v_mov_b32_e32 v4, 0x24300000
	v_cmp_lt_u32_e32 vcc, s0, v2
	v_mov_b32_e32 v5, 0x28300000
	v_mov_b32_e32 v17, v1
	v_and_b32_e32 v18, 0x3e000, v124
	v_cndmask_b32_e32 v16, v4, v5, vcc
	v_cmp_ne_u32_e64 s[0:1], 0, v18
	v_lshl_add_u64 v[16:17], s[4:5], 0, v[16:17]
	v_lshl_add_u64 v[16:17], v[124:125], 1, v[16:17]
	s_waitcnt vmcnt(15)
	v_cvt_pk_bf16_f32 v100, v60, v61
	v_cvt_pk_bf16_f32 v101, v62, v63
	s_nop 0
	global_store_dwordx2 v[16:17], v[100:101], off
	s_and_saveexec_b64 s[10:11], s[0:1]
	s_cbranch_execz .Lcc_skip_u8_10
	v_mov_b32_e32 v4, 0x6222000
	v_mov_b32_e32 v5, 0xe222000
	v_cndmask_b32_e32 v4, v4, v5, vcc
	v_mov_b32_e32 v5, v1
	v_lshl_add_u64 v[4:5], s[6:7], 0, v[4:5]
	v_lshl_add_u64 v[4:5], v[124:125], 2, v[4:5]
	v_add_co_u32_e32 v4, vcc, 0xffff8000, v4
	s_nop 1
	v_addc_co_u32_e32 v5, vcc, -1, v5, vcc
	s_nop 0
	global_store_dwordx4 v[4:5], v[60:63], off
.Lcc_skip_u8_10:
	s_or_b64 exec, exec, s[10:11]
	v_add3_u32 v2, v9, s16, 32
	s_mov_b32 s0, 0xfffff
	v_mov_b32_e32 v4, 0x24300000
	v_cmp_lt_u32_e32 vcc, s0, v2
	v_mov_b32_e32 v5, 0x28300000
	v_mov_b32_e32 v17, v1
	v_and_b32_e32 v18, 0x3e000, v126
	v_cndmask_b32_e32 v16, v4, v5, vcc
	v_cmp_ne_u32_e64 s[0:1], 0, v18
	v_lshl_add_u64 v[16:17], s[4:5], 0, v[16:17]
	v_lshl_add_u64 v[16:17], v[126:127], 1, v[16:17]
	s_waitcnt vmcnt(15)
	v_cvt_pk_bf16_f32 v102, v64, v65
	v_cvt_pk_bf16_f32 v103, v66, v67
	s_nop 0
	global_store_dwordx2 v[16:17], v[102:103], off
	s_and_saveexec_b64 s[10:11], s[0:1]
	s_cbranch_execz .Lcc_skip_u8_11
	v_mov_b32_e32 v4, 0x6222000
	v_mov_b32_e32 v5, 0xe222000
	v_cndmask_b32_e32 v4, v4, v5, vcc
	v_mov_b32_e32 v5, v1
	v_lshl_add_u64 v[4:5], s[6:7], 0, v[4:5]
	v_lshl_add_u64 v[4:5], v[126:127], 2, v[4:5]
	v_add_co_u32_e32 v4, vcc, 0xffff8000, v4
	s_nop 1
	v_addc_co_u32_e32 v5, vcc, -1, v5, vcc
	s_nop 0
	global_store_dwordx4 v[4:5], v[64:67], off
.Lcc_skip_u8_11:
	s_or_b64 exec, exec, s[10:11]
	s_add_u32 s16, s16, s13
	v_add3_u32 v2, v9, s16, 0
	s_mov_b32 s0, 0xfffff
	v_mov_b32_e32 v4, 0x24300000
	v_cmp_lt_u32_e32 vcc, s0, v2
	v_mov_b32_e32 v5, 0x28300000
	v_mov_b32_e32 v17, v1
	v_and_b32_e32 v18, 0x3e000, v128
	v_cndmask_b32_e32 v16, v4, v5, vcc
	v_cmp_ne_u32_e64 s[0:1], 0, v18
	v_lshl_add_u64 v[16:17], s[4:5], 0, v[16:17]
	v_lshl_add_u64 v[16:17], v[128:129], 1, v[16:17]
	s_waitcnt vmcnt(15)
	v_cvt_pk_bf16_f32 v12, v68, v69
	v_cvt_pk_bf16_f32 v13, v70, v71
	s_nop 0
	global_store_dwordx2 v[16:17], v[12:13], off
	s_and_saveexec_b64 s[10:11], s[0:1]
	s_cbranch_execz .Lcc_skip_u8_12
	v_mov_b32_e32 v4, 0x6222000
	v_mov_b32_e32 v5, 0xe222000
	v_cndmask_b32_e32 v4, v4, v5, vcc
	v_mov_b32_e32 v5, v1
	v_lshl_add_u64 v[4:5], s[6:7], 0, v[4:5]
	v_lshl_add_u64 v[4:5], v[128:129], 2, v[4:5]
	v_add_co_u32_e32 v4, vcc, 0xffff8000, v4
	s_nop 1
	v_addc_co_u32_e32 v5, vcc, -1, v5, vcc
	s_nop 0
	global_store_dwordx4 v[4:5], v[68:71], off
.Lcc_skip_u8_12:
	s_or_b64 exec, exec, s[10:11]
	v_add3_u32 v2, v9, s16, 32
	s_mov_b32 s0, 0xfffff
	v_mov_b32_e32 v4, 0x24300000
	v_cmp_lt_u32_e32 vcc, s0, v2
	v_mov_b32_e32 v5, 0x28300000
	v_mov_b32_e32 v17, v1
	v_and_b32_e32 v18, 0x3e000, v130
	v_cndmask_b32_e32 v16, v4, v5, vcc
	v_cmp_ne_u32_e64 s[0:1], 0, v18
	v_lshl_add_u64 v[16:17], s[4:5], 0, v[16:17]
	v_lshl_add_u64 v[16:17], v[130:131], 1, v[16:17]
	s_waitcnt vmcnt(15)
	v_cvt_pk_bf16_f32 v14, v72, v73
	v_cvt_pk_bf16_f32 v15, v74, v75
	s_nop 0
	global_store_dwordx2 v[16:17], v[14:15], off
	s_and_saveexec_b64 s[10:11], s[0:1]
	s_cbranch_execz .Lcc_skip_u8_13
	v_mov_b32_e32 v4, 0x6222000
	v_mov_b32_e32 v5, 0xe222000
	v_cndmask_b32_e32 v4, v4, v5, vcc
	v_mov_b32_e32 v5, v1
	v_lshl_add_u64 v[4:5], s[6:7], 0, v[4:5]
	v_lshl_add_u64 v[4:5], v[130:131], 2, v[4:5]
	v_add_co_u32_e32 v4, vcc, 0xffff8000, v4
	s_nop 1
	v_addc_co_u32_e32 v5, vcc, -1, v5, vcc
	s_nop 0
	global_store_dwordx4 v[4:5], v[72:75], off
.Lcc_skip_u8_13:
	s_or_b64 exec, exec, s[10:11]
	s_add_u32 s16, s16, s13
	v_add3_u32 v2, v9, s16, 0
	s_mov_b32 s0, 0xfffff
	v_mov_b32_e32 v4, 0x24300000
	v_cmp_lt_u32_e32 vcc, s0, v2
	v_mov_b32_e32 v5, 0x28300000
	v_mov_b32_e32 v17, v1
	v_and_b32_e32 v18, 0x3e000, v132
	v_cndmask_b32_e32 v16, v4, v5, vcc
	v_cmp_ne_u32_e64 s[0:1], 0, v18
	v_lshl_add_u64 v[16:17], s[4:5], 0, v[16:17]
	v_lshl_add_u64 v[16:17], v[132:133], 1, v[16:17]
	s_waitcnt vmcnt(15)
	v_cvt_pk_bf16_f32 v100, v76, v77
	v_cvt_pk_bf16_f32 v101, v78, v79
	s_nop 0
	global_store_dwordx2 v[16:17], v[100:101], off
	s_and_saveexec_b64 s[10:11], s[0:1]
	s_cbranch_execz .Lcc_skip_u8_14
	v_mov_b32_e32 v4, 0x6222000
	v_mov_b32_e32 v5, 0xe222000
	v_cndmask_b32_e32 v4, v4, v5, vcc
	v_mov_b32_e32 v5, v1
	v_lshl_add_u64 v[4:5], s[6:7], 0, v[4:5]
	v_lshl_add_u64 v[4:5], v[132:133], 2, v[4:5]
	v_add_co_u32_e32 v4, vcc, 0xffff8000, v4
	s_nop 1
	v_addc_co_u32_e32 v5, vcc, -1, v5, vcc
	s_nop 0
	global_store_dwordx4 v[4:5], v[76:79], off
.Lcc_skip_u8_14:
	s_or_b64 exec, exec, s[10:11]
	v_add3_u32 v2, v9, s16, 32
	s_mov_b32 s0, 0xfffff
	v_mov_b32_e32 v4, 0x24300000
	v_cmp_lt_u32_e32 vcc, s0, v2
	v_mov_b32_e32 v5, 0x28300000
	v_mov_b32_e32 v17, v1
	v_and_b32_e32 v18, 0x3e000, v134
	v_cndmask_b32_e32 v16, v4, v5, vcc
	v_cmp_ne_u32_e64 s[0:1], 0, v18
	v_lshl_add_u64 v[16:17], s[4:5], 0, v[16:17]
	v_lshl_add_u64 v[16:17], v[134:135], 1, v[16:17]
	s_waitcnt vmcnt(15)
	v_cvt_pk_bf16_f32 v102, v80, v81
	v_cvt_pk_bf16_f32 v103, v82, v83
	s_nop 0
	global_store_dwordx2 v[16:17], v[102:103], off
	s_and_saveexec_b64 s[10:11], s[0:1]
	s_cbranch_execz .Lcc_skip_u8_15
	v_mov_b32_e32 v4, 0x6222000
	v_mov_b32_e32 v5, 0xe222000
	v_cndmask_b32_e32 v4, v4, v5, vcc
	v_mov_b32_e32 v5, v1
	v_lshl_add_u64 v[4:5], s[6:7], 0, v[4:5]
	v_lshl_add_u64 v[4:5], v[134:135], 2, v[4:5]
	v_add_co_u32_e32 v4, vcc, 0xffff8000, v4
	s_nop 1
	v_addc_co_u32_e32 v5, vcc, -1, v5, vcc
	s_nop 0
	global_store_dwordx4 v[4:5], v[80:83], off

; __device__ __forceinline__ void cache_convert(const Params& P, int l, int pct0, int pct1, int part, int nparts) {
;     ...
; #pragma unroll 8
;     for (unsigned gi = g0 + (unsigned)part * 512u + tid; gi < g1; gi += (unsigned)nparts * 512u) {
;         const bool isv = gi >= NGL; const unsigned e = (isv ? gi - NGL : gi) * 8u; const int key = (int)((e >> 9) & 511u);
;         const float* src = (isv ? cv : ck) + e;
;         const f32x4 k0 = *(const f32x4*)src, k1 = *(const f32x4*)(src + 4);
;         *(bf16x8*)((isv ? vb : kb) + e) = pack8v(k0, k1);
;         if (key >= 16) { float* d = (isv ? ov : ok) + e - 16 * 512; *(f32x4*)d = k0; *(f32x4*)(d + 4) = k1; }
.Lcc_try4:
	v_readlane_b32 s16, v10, 63
	s_mul_i32 s17, s13, 3
	s_add_u32 s16, s16, s17
	s_cmp_lt_u32 s16, s12
	s_cbranch_scc0 .Lcc_try2
	v_readlane_b32 s22, v253, 61
	v_readlane_b32 s23, v253, 62
	v_readlane_b32 s24, v253, 63
	v_readlane_b32 s25, v254, 0
	s_mov_b64 s[18:19], s[22:23]
	s_mov_b64 s[20:21], s[24:25]
	s_mov_b32 s0, 0xfffff
	s_mov_b32 s16, 0
	v_and_b32_e32 v2, 63, v208
	v_add_u32_e32 v3, 1, v2
	v_lshrrev_b32_e32 v3, 1, v3
	v_and_b32_e32 v2, 1, v2
	v_sub_u32_e32 v9, v10, v3
	v_lshlrev_b32_e32 v19, 2, v2
	v_mov_b32_e32 v105, 0
	v_mov_b32_e32 v107, 0
	v_mov_b32_e32 v109, 0
	v_mov_b32_e32 v111, 0
	v_mov_b32_e32 v113, 0
	v_mov_b32_e32 v115, 0
	v_mov_b32_e32 v117, 0
	v_mov_b32_e32 v119, 0
	v_add3_u32 v2, v9, s16, 0
	s_nop 0
	v_cmp_lt_u32_e32 vcc, s0, v2
	v_lshl_add_u32 v3, v2, 3, v19
	v_mov_b32_e32 v5, s19
	v_add_u32_e32 v4, 0xff800000, v3
	v_mov_b32_e32 v6, s21
	v_cndmask_b32_e32 v104, v3, v4, vcc
	v_cndmask_b32_e32 v7, v5, v6, vcc
	v_mov_b32_e32 v5, s18
	v_mov_b32_e32 v8, s20
	v_cndmask_b32_e32 v6, v5, v8, vcc
	v_lshl_add_u64 v[6:7], v[6:7], 0, s[62:63]
	v_lshl_add_u64 v[6:7], v[104:105], 2, v[6:7]
	global_load_dwordx4 v[20:23], v[6:7], off
	v_add3_u32 v2, v9, s16, 32
	s_nop 0
	v_cmp_lt_u32_e32 vcc, s0, v2
	v_lshl_add_u32 v3, v2, 3, v19
	v_mov_b32_e32 v5, s19
	v_add_u32_e32 v4, 0xff800000, v3
	v_mov_b32_e32 v6, s21
	v_cndmask_b32_e32 v106, v3, v4, vcc
	v_cndmask_b32_e32 v7, v5, v6, vcc
	v_mov_b32_e32 v5, s18
	v_mov_b32_e32 v8, s20
	v_cndmask_b32_e32 v6, v5, v8, vcc
	v_lshl_add_u64 v[6:7], v[6:7], 0, s[62:63]
	v_lshl_add_u64 v[6:7], v[106:107], 2, v[6:7]
	global_load_dwordx4 v[24:27], v[6:7], off
	s_add_u32 s16, s16, s13
	v_add3_u32 v2, v9, s16, 0
	s_nop 0
	v_cmp_lt_u32_e32 vcc, s0, v2
	v_lshl_add_u32 v3, v2, 3, v19
	v_mov_b32_e32 v5, s19
	v_add_u32_e32 v4, 0xff800000, v3
	v_mov_b32_e32 v6, s21
	v_cndmask_b32_e32 v108, v3, v4, vcc
	v_cndmask_b32_e32 v7, v5, v6, vcc
	v_mov_b32_e32 v5, s18
	v_mov_b32_e32 v8, s20
	v_cndmask_b32_e32 v6, v5, v8, vcc
	v_lshl_add_u64 v[6:7], v[6:7], 0, s[62:63]
	v_lshl_add_u64 v[6:7], v[108:109], 2, v[6:7]
	global_load_dwordx4 v[28:31], v[6:7], off
	v_add3_u32 v2, v9, s16, 32
	s_nop 0
	v_cmp_lt_u32_e32 vcc, s0, v2
	v_lshl_add_u32 v3, v2, 3, v19
	v_mov_b32_e32 v5, s19
	v_add_u32_e32 v4, 0xff800000, v3
	v_mov_b32_e32 v6, s21
	v_cndmask_b32_e32 v110, v3, v4, vcc
	v_cndmask_b32_e32 v7, v5, v6, vcc
	v_mov_b32_e32 v5, s18
	v_mov_b32_e32 v8, s20
	v_cndmask_b32_e32 v6, v5, v8, vcc
	v_lshl_add_u64 v[6:7], v[6:7], 0, s[62:63]
	v_lshl_add_u64 v[6:7], v[110:111], 2, v[6:7]
	global_load_dwordx4 v[32:35], v[6:7], off
	s_add_u32 s16, s16, s13
	v_add3_u32 v2, v9, s16, 0
	s_nop 0
	v_cmp_lt_u32_e32 vcc, s0, v2
	v_lshl_add_u32 v3, v2, 3, v19
	v_mov_b32_e32 v5, s19
	v_add_u32_e32 v4, 0xff800000, v3
	v_mov_b32_e32 v6, s21
	v_cndmask_b32_e32 v112, v3, v4, vcc
	v_cndmask_b32_e32 v7, v5, v6, vcc
	v_mov_b32_e32 v5, s18
	v_mov_b32_e32 v8, s20
	v_cndmask_b32_e32 v6, v5, v8, vcc
	v_lshl_add_u64 v[6:7], v[6:7], 0, s[62:63]
	v_lshl_add_u64 v[6:7], v[112:113], 2, v[6:7]
	global_load_dwordx4 v[36:39], v[6:7], off
	v_add3_u32 v2, v9, s16, 32
	s_nop 0
	v_cmp_lt_u32_e32 vcc, s0, v2
	v_lshl_add_u32 v3, v2, 3, v19
	v_mov_b32_e32 v5, s19
	v_add_u32_e32 v4, 0xff800000, v3
	v_mov_b32_e32 v6, s21
	v_cndmask_b32_e32 v114, v3, v4, vcc
	v_cndmask_b32_e32 v7, v5, v6, vcc
	v_mov_b32_e32 v5, s18
	v_mov_b32_e32 v8, s20
	v_cndmask_b32_e32 v6, v5, v8, vcc
	v_lshl_add_u64 v[6:7], v[6:7], 0, s[62:63]
	v_lshl_add_u64 v[6:7], v[114:115], 2, v[6:7]
	global_load_dwordx4 v[40:43], v[6:7], off
	s_add_u32 s16, s16, s13
	v_add3_u32 v2, v9, s16, 0
	s_nop 0
	v_cmp_lt_u32_e32 vcc, s0, v2
	v_lshl_add_u32 v3, v2, 3, v19
	v_mov_b32_e32 v5, s19
	v_add_u32_e32 v4, 0xff800000, v3
	v_mov_b32_e32 v6, s21
	v_cndmask_b32_e32 v116, v3, v4, vcc
	v_cndmask_b32_e32 v7, v5, v6, vcc
	v_mov_b32_e32 v5, s18
	v_mov_b32_e32 v8, s20
	v_cndmask_b32_e32 v6, v5, v8, vcc
	v_lshl_add_u64 v[6:7], v[6:7], 0, s[62:63]
	v_lshl_add_u64 v[6:7], v[116:117], 2, v[6:7]
	global_load_dwordx4 v[44:47], v[6:7], off
	v_add3_u32 v2, v9, s16, 32
	s_nop 0
	v_cmp_lt_u32_e32 vcc, s0, v2
	v_lshl_add_u32 v3, v2, 3, v19
	v_mov_b32_e32 v5, s19
	v_add_u32_e32 v4, 0xff800000, v3
	v_mov_b32_e32 v6, s21
	v_cndmask_b32_e32 v118, v3, v4, vcc
	v_cndmask_b32_e32 v7, v5, v6, vcc
	v_mov_b32_e32 v5, s18
	v_mov_b32_e32 v8, s20
	v_cndmask_b32_e32 v6, v5, v8, vcc
	v_lshl_add_u64 v[6:7], v[6:7], 0, s[62:63]
	v_lshl_add_u64 v[6:7], v[118:119], 2, v[6:7]
	global_load_dwordx4 v[48:51], v[6:7], off
	s_mov_b32 s16, 0
	v_add3_u32 v2, v9, s16, 0
	s_mov_b32 s0, 0xfffff
	v_mov_b32_e32 v4, 0x24300000
	v_cmp_lt_u32_e32 vcc, s0, v2
	v_mov_b32_e32 v5, 0x28300000
	v_mov_b32_e32 v17, v1
	v_and_b32_e32 v18, 0x3e000, v104
	v_cndmask_b32_e32 v16, v4, v5, vcc
	v_cmp_ne_u32_e64 s[0:1], 0, v18
	v_lshl_add_u64 v[16:17], s[4:5], 0, v[16:17]
	v_lshl_add_u64 v[16:17], v[104:105], 1, v[16:17]
	s_waitcnt vmcnt(7)
	v_cvt_pk_bf16_f32 v12, v20, v21
	v_cvt_pk_bf16_f32 v13, v22, v23
	s_nop 0
	global_store_dwordx2 v[16:17], v[12:13], off
	s_and_saveexec_b64 s[10:11], s[0:1]
	s_cbranch_execz .Lcc_skip_u4_0
	v_mov_b32_e32 v4, 0x6222000
	v_mov_b32_e32 v5, 0xe222000
	v_cndmask_b32_e32 v4, v4, v5, vcc
	v_mov_b32_e32 v5, v1
	v_lshl_add_u64 v[4:5], s[6:7], 0, v[4:5]
	v_lshl_add_u64 v[4:5], v[104:105], 2, v[4:5]
	v_add_co_u32_e32 v4, vcc, 0xffff8000, v4
	s_nop 1
	v_addc_co_u32_e32 v5, vcc, -1, v5, vcc
	s_nop 0
	global_store_dwordx4 v[4:5], v[20:23], off
; __device__ __forceinline__ void cache_convert(const Params& P, int l, int pct0, int pct1, int part, int nparts) {
;     ...
;         const bool isv = gi >= NGL; const unsigned e = (isv ? gi - NGL : gi) * 8u; const int key = (int)((e >> 9) & 511u);
;         const float* src = (isv ? cv : ck) + e;
;         const f32x4 k0 = *(const f32x4*)src, k1 = *(const f32x4*)(src + 4);
;         *(bf16x8*)((isv ? vb : kb) + e) = pack8v(k0, k1);
;         if (key >= 16) { float* d = (isv ? ov : ok) + e - 16 * 512; *(f32x4*)d = k0; *(f32x4*)(d + 4) = k1; }
.Lcc_skip_u4_0:
	s_or_b64 exec, exec, s[10:11]
	v_add3_u32 v2, v9, s16, 32
	s_mov_b32 s0, 0xfffff
	v_mov_b32_e32 v4, 0x24300000
	v_cmp_lt_u32_e32 vcc, s0, v2
	v_mov_b32_e32 v5, 0x28300000
	v_mov_b32_e32 v17, v1
	v_and_b32_e32 v18, 0x3e000, v106
	v_cndmask_b32_e32 v16, v4, v5, vcc
	v_cmp_ne_u32_e64 s[0:1], 0, v18
	v_lshl_add_u64 v[16:17], s[4:5], 0, v[16:17]
	v_lshl_add_u64 v[16:17], v[106:107], 1, v[16:17]
	s_waitcnt vmcnt(7)
	v_cvt_pk_bf16_f32 v14, v24, v25
	v_cvt_pk_bf16_f32 v15, v26, v27
	s_nop 0
	global_store_dwordx2 v[16:17], v[14:15], off
	s_and_saveexec_b64 s[10:11], s[0:1]
	s_cbranch_execz .Lcc_skip_u4_1
	v_mov_b32_e32 v4, 0x6222000
	v_mov_b32_e32 v5, 0xe222000
	v_cndmask_b32_e32 v4, v4, v5, vcc
	v_mov_b32_e32 v5, v1
	v_lshl_add_u64 v[4:5], s[6:7], 0, v[4:5]
	v_lshl_add_u64 v[4:5], v[106:107], 2, v[4:5]
	v_add_co_u32_e32 v4, vcc, 0xffff8000, v4
	s_nop 1
	v_addc_co_u32_e32 v5, vcc, -1, v5, vcc
	s_nop 0
	global_store_dwordx4 v[4:5], v[24:27], off
.Lcc_skip_u4_1:
	s_or_b64 exec, exec, s[10:11]
	s_add_u32 s16, s16, s13
	v_add3_u32 v2, v9, s16, 0
	s_mov_b32 s0, 0xfffff
	v_mov_b32_e32 v4, 0x24300000
	v_cmp_lt_u32_e32 vcc, s0, v2
	v_mov_b32_e32 v5, 0x28300000
	v_mov_b32_e32 v17, v1
	v_and_b32_e32 v18, 0x3e000, v108
	v_cndmask_b32_e32 v16, v4, v5, vcc
	v_cmp_ne_u32_e64 s[0:1], 0, v18
	v_lshl_add_u64 v[16:17], s[4:5], 0, v[16:17]
	v_lshl_add_u64 v[16:17], v[108:109], 1, v[16:17]
	s_waitcnt vmcnt(7)
	v_cvt_pk_bf16_f32 v100, v28, v29
	v_cvt_pk_bf16_f32 v101, v30, v31
	s_nop 0
	global_store_dwordx2 v[16:17], v[100:101], off
	s_and_saveexec_b64 s[10:11], s[0:1]
	s_cbranch_execz .Lcc_skip_u4_2
	v_mov_b32_e32 v4, 0x6222000
	v_mov_b32_e32 v5, 0xe222000
	v_cndmask_b32_e32 v4, v4, v5, vcc
	v_mov_b32_e32 v5, v1
	v_lshl_add_u64 v[4:5], s[6:7], 0, v[4:5]
	v_lshl_add_u64 v[4:5], v[108:109], 2, v[4:5]
	v_add_co_u32_e32 v4, vcc, 0xffff8000, v4
	s_nop 1
	v_addc_co_u32_e32 v5, vcc, -1, v5, vcc
	s_nop 0
	global_store_dwordx4 v[4:5], v[28:31], off
.Lcc_skip_u4_2:
	s_or_b64 exec, exec, s[10:11]
	v_add3_u32 v2, v9, s16, 32
	s_mov_b32 s0, 0xfffff
	v_mov_b32_e32 v4, 0x24300000
	v_cmp_lt_u32_e32 vcc, s0, v2
	v_mov_b32_e32 v5, 0x28300000
	v_mov_b32_e32 v17, v1
	v_and_b32_e32 v18, 0x3e000, v110
	v_cndmask_b32_e32 v16, v4, v5, vcc
	v_cmp_ne_u32_e64 s[0:1], 0, v18
	v_lshl_add_u64 v[16:17], s[4:5], 0, v[16:17]
	v_lshl_add_u64 v[16:17], v[110:111], 1, v[16:17]
	s_waitcnt vmcnt(7)
	v_cvt_pk_bf16_f32 v102, v32, v33
	v_cvt_pk_bf16_f32 v103, v34, v35
	s_nop 0
	global_store_dwordx2 v[16:17], v[102:103], off
	s_and_saveexec_b64 s[10:11], s[0:1]
	s_cbranch_execz .Lcc_skip_u4_3
	v_mov_b32_e32 v4, 0x6222000
	v_mov_b32_e32 v5, 0xe222000
	v_cndmask_b32_e32 v4, v4, v5, vcc
	v_mov_b32_e32 v5, v1
	v_lshl_add_u64 v[4:5], s[6:7], 0, v[4:5]
	v_lshl_add_u64 v[4:5], v[110:111], 2, v[4:5]
	v_add_co_u32_e32 v4, vcc, 0xffff8000, v4
	s_nop 1
	v_addc_co_u32_e32 v5, vcc, -1, v5, vcc
	s_nop 0
	global_store_dwordx4 v[4:5], v[32:35], off
.Lcc_skip_u4_3:
	s_or_b64 exec, exec, s[10:11]
	s_add_u32 s16, s16, s13
	v_add3_u32 v2, v9, s16, 0
	s_mov_b32 s0, 0xfffff
	v_mov_b32_e32 v4, 0x24300000
	v_cmp_lt_u32_e32 vcc, s0, v2
	v_mov_b32_e32 v5, 0x28300000
	v_mov_b32_e32 v17, v1
	v_and_b32_e32 v18, 0x3e000, v112
	v_cndmask_b32_e32 v16, v4, v5, vcc
	v_cmp_ne_u32_e64 s[0:1], 0, v18
	v_lshl_add_u64 v[16:17], s[4:5], 0, v[16:17]
	v_lshl_add_u64 v[16:17], v[112:113], 1, v[16:17]
	s_waitcnt vmcnt(7)
	v_cvt_pk_bf16_f32 v12, v36, v37
	v_cvt_pk_bf16_f32 v13, v38, v39
	s_nop 0
	global_store_dwordx2 v[16:17], v[12:13], off
	s_and_saveexec_b64 s[10:11], s[0:1]
	s_cbranch_execz .Lcc_skip_u4_4
	v_mov_b32_e32 v4, 0x6222000
	v_mov_b32_e32 v5, 0xe222000
	v_cndmask_b32_e32 v4, v4, v5, vcc
	v_mov_b32_e32 v5, v1
	v_lshl_add_u64 v[4:5], s[6:7], 0, v[4:5]
	v_lshl_add_u64 v[4:5], v[112:113], 2, v[4:5]
	v_add_co_u32_e32 v4, vcc, 0xffff8000, v4
	s_nop 1
	v_addc_co_u32_e32 v5, vcc, -1, v5, vcc
	s_nop 0
	global_store_dwordx4 v[4:5], v[36:39], off
.Lcc_skip_u4_4:
	s_or_b64 exec, exec, s[10:11]
	v_add3_u32 v2, v9, s16, 32
	s_mov_b32 s0, 0xfffff
	v_mov_b32_e32 v4, 0x24300000
	v_cmp_lt_u32_e32 vcc, s0, v2
	v_mov_b32_e32 v5, 0x28300000
	v_mov_b32_e32 v17, v1
	v_and_b32_e32 v18, 0x3e000, v114
	v_cndmask_b32_e32 v16, v4, v5, vcc
	v_cmp_ne_u32_e64 s[0:1], 0, v18
	v_lshl_add_u64 v[16:17], s[4:5], 0, v[16:17]
	v_lshl_add_u64 v[16:17], v[114:115], 1, v[16:17]
	s_waitcnt vmcnt(7)
	v_cvt_pk_bf16_f32 v14, v40, v41
	v_cvt_pk_bf16_f32 v15, v42, v43
	s_nop 0
	global_store_dwordx2 v[16:17], v[14:15], off
	s_and_saveexec_b64 s[10:11], s[0:1]
	s_cbranch_execz .Lcc_skip_u4_5
	v_mov_b32_e32 v4, 0x6222000
	v_mov_b32_e32 v5, 0xe222000
	v_cndmask_b32_e32 v4, v4, v5, vcc
	v_mov_b32_e32 v5, v1
	v_lshl_add_u64 v[4:5], s[6:7], 0, v[4:5]
	v_lshl_add_u64 v[4:5], v[114:115], 2, v[4:5]
	v_add_co_u32_e32 v4, vcc, 0xffff8000, v4
	s_nop 1
	v_addc_co_u32_e32 v5, vcc, -1, v5, vcc
	s_nop 0
	global_store_dwordx4 v[4:5], v[40:43], off
.Lcc_skip_u4_5:
	s_or_b64 exec, exec, s[10:11]
	s_add_u32 s16, s16, s13
	v_add3_u32 v2, v9, s16, 0
	s_mov_b32 s0, 0xfffff
	v_mov_b32_e32 v4, 0x24300000
	v_cmp_lt_u32_e32 vcc, s0, v2
	v_mov_b32_e32 v5, 0x28300000
	v_mov_b32_e32 v17, v1
	v_and_b32_e32 v18, 0x3e000, v116
	v_cndmask_b32_e32 v16, v4, v5, vcc
	v_cmp_ne_u32_e64 s[0:1], 0, v18
	v_lshl_add_u64 v[16:17], s[4:5], 0, v[16:17]
	v_lshl_add_u64 v[16:17], v[116:117], 1, v[16:17]
	s_waitcnt vmcnt(7)
	v_cvt_pk_bf16_f32 v100, v44, v45
	v_cvt_pk_bf16_f32 v101, v46, v47
	s_nop 0
	global_store_dwordx2 v[16:17], v[100:101], off
	s_and_saveexec_b64 s[10:11], s[0:1]
	s_cbranch_execz .Lcc_skip_u4_6
	v_mov_b32_e32 v4, 0x6222000
	v_mov_b32_e32 v5, 0xe222000
	v_cndmask_b32_e32 v4, v4, v5, vcc
	v_mov_b32_e32 v5, v1
	v_lshl_add_u64 v[4:5], s[6:7], 0, v[4:5]
	v_lshl_add_u64 v[4:5], v[116:117], 2, v[4:5]
	v_add_co_u32_e32 v4, vcc, 0xffff8000, v4
	s_nop 1
	v_addc_co_u32_e32 v5, vcc, -1, v5, vcc
	s_nop 0
	global_store_dwordx4 v[4:5], v[44:47], off
; __device__ __forceinline__ void cache_convert(const Params& P, int l, int pct0, int pct1, int part, int nparts) {
;     ...
; #pragma unroll 8
;     for (unsigned gi = g0 + (unsigned)part * 512u + tid; gi < g1; gi += (unsigned)nparts * 512u) {
;         const bool isv = gi >= NGL; const unsigned e = (isv ? gi - NGL : gi) * 8u; const int key = (int)((e >> 9) & 511u);
;         const float* src = (isv ? cv : ck) + e;
;         const f32x4 k0 = *(const f32x4*)src, k1 = *(const f32x4*)(src + 4);
;         *(bf16x8*)((isv ? vb : kb) + e) = pack8v(k0, k1);
;         if (key >= 16) { float* d = (isv ? ov : ok) + e - 16 * 512; *(f32x4*)d = k0; *(f32x4*)(d + 4) = k1; }
.Lcc_skip_u4_6:
	s_or_b64 exec, exec, s[10:11]
	v_add3_u32 v2, v9, s16, 32
	s_mov_b32 s0, 0xfffff
	v_mov_b32_e32 v4, 0x24300000
	v_cmp_lt_u32_e32 vcc, s0, v2
	v_mov_b32_e32 v5, 0x28300000
	v_mov_b32_e32 v17, v1
	v_and_b32_e32 v18, 0x3e000, v118
	v_cndmask_b32_e32 v16, v4, v5, vcc
	v_cmp_ne_u32_e64 s[0:1], 0, v18
	v_lshl_add_u64 v[16:17], s[4:5], 0, v[16:17]
	v_lshl_add_u64 v[16:17], v[118:119], 1, v[16:17]
	s_waitcnt vmcnt(7)
	v_cvt_pk_bf16_f32 v102, v48, v49
	v_cvt_pk_bf16_f32 v103, v50, v51
	s_nop 0
	global_store_dwordx2 v[16:17], v[102:103], off
	s_and_saveexec_b64 s[10:11], s[0:1]
	s_cbranch_execz .Lcc_skip_u4_7
	v_mov_b32_e32 v4, 0x6222000
	v_mov_b32_e32 v5, 0xe222000
	v_cndmask_b32_e32 v4, v4, v5, vcc
	v_mov_b32_e32 v5, v1
	v_lshl_add_u64 v[4:5], s[6:7], 0, v[4:5]
	v_lshl_add_u64 v[4:5], v[118:119], 2, v[4:5]
	v_add_co_u32_e32 v4, vcc, 0xffff8000, v4
	s_nop 1
	v_addc_co_u32_e32 v5, vcc, -1, v5, vcc
	s_nop 0
	global_store_dwordx4 v[4:5], v[48:51], off
.Lcc_skip_u4_7:
	s_or_b64 exec, exec, s[10:11]
	s_mul_i32 s16, s13, 3
	s_mul_i32 s17, s14, 3
	v_add_u32_e32 v10, s16, v10
	v_add_u32_e32 v11, s17, v11
	s_mov_b64 s[10:11], exec
	s_branch .LBB0_678
.Lcc_try2:
	v_readlane_b32 s16, v10, 63
	s_mul_i32 s17, s13, 1
	s_add_u32 s16, s16, s17
	s_cmp_lt_u32 s16, s12
	s_cbranch_scc0 .Lcc_slow
	v_readlane_b32 s22, v253, 61
	v_readlane_b32 s23, v253, 62
	v_readlane_b32 s24, v253, 63
	v_readlane_b32 s25, v254, 0
	s_mov_b64 s[18:19], s[22:23]
	s_mov_b64 s[20:21], s[24:25]
	s_mov_b32 s0, 0xfffff
	s_mov_b32 s16, 0
	v_and_b32_e32 v2, 63, v208
	v_add_u32_e32 v3, 1, v2
	v_lshrrev_b32_e32 v3, 1, v3
	v_and_b32_e32 v2, 1, v2
	v_sub_u32_e32 v9, v10, v3
	v_lshlrev_b32_e32 v19, 2, v2
	v_mov_b32_e32 v105, 0
	v_mov_b32_e32 v107, 0
	v_mov_b32_e32 v109, 0
	v_mov_b32_e32 v111, 0
	v_add3_u32 v2, v9, s16, 0
	s_nop 0
	v_cmp_lt_u32_e32 vcc, s0, v2
	v_lshl_add_u32 v3, v2, 3, v19
	v_mov_b32_e32 v5, s19
	v_add_u32_e32 v4, 0xff800000, v3
	v_mov_b32_e32 v6, s21
	v_cndmask_b32_e32 v104, v3, v4, vcc
	v_cndmask_b32_e32 v7, v5, v6, vcc
	v_mov_b32_e32 v5, s18
	v_mov_b32_e32 v8, s20
	v_cndmask_b32_e32 v6, v5, v8, vcc
	v_lshl_add_u64 v[6:7], v[6:7], 0, s[62:63]
	v_lshl_add_u64 v[6:7], v[104:105], 2, v[6:7]
	global_load_dwordx4 v[20:23], v[6:7], off
	v_add3_u32 v2, v9, s16, 32
	s_nop 0
	v_cmp_lt_u32_e32 vcc, s0, v2
	v_lshl_add_u32 v3, v2, 3, v19
	v_mov_b32_e32 v5, s19
	v_add_u32_e32 v4, 0xff800000, v3
	v_mov_b32_e32 v6, s21
	v_cndmask_b32_e32 v106, v3, v4, vcc
	v_cndmask_b32_e32 v7, v5, v6, vcc
	v_mov_b32_e32 v5, s18
	v_mov_b32_e32 v8, s20
	v_cndmask_b32_e32 v6, v5, v8, vcc
	v_lshl_add_u64 v[6:7], v[6:7], 0, s[62:63]
	v_lshl_add_u64 v[6:7], v[106:107], 2, v[6:7]
	global_load_dwordx4 v[24:27], v[6:7], off
	s_add_u32 s16, s16, s13
	v_add3_u32 v2, v9, s16, 0
	s_nop 0
	v_cmp_lt_u32_e32 vcc, s0, v2
	v_lshl_add_u32 v3, v2, 3, v19
	v_mov_b32_e32 v5, s19
	v_add_u32_e32 v4, 0xff800000, v3
	v_mov_b32_e32 v6, s21
	v_cndmask_b32_e32 v108, v3, v4, vcc
	v_cndmask_b32_e32 v7, v5, v6, vcc
	v_mov_b32_e32 v5, s18
	v_mov_b32_e32 v8, s20
	v_cndmask_b32_e32 v6, v5, v8, vcc
	v_lshl_add_u64 v[6:7], v[6:7], 0, s[62:63]
	v_lshl_add_u64 v[6:7], v[108:109], 2, v[6:7]
	global_load_dwordx4 v[28:31], v[6:7], off
	v_add3_u32 v2, v9, s16, 32
	s_nop 0
	v_cmp_lt_u32_e32 vcc, s0, v2
	v_lshl_add_u32 v3, v2, 3, v19
	v_mov_b32_e32 v5, s19
	v_add_u32_e32 v4, 0xff800000, v3
	v_mov_b32_e32 v6, s21
	v_cndmask_b32_e32 v110, v3, v4, vcc
	v_cndmask_b32_e32 v7, v5, v6, vcc
	v_mov_b32_e32 v5, s18
	v_mov_b32_e32 v8, s20
	v_cndmask_b32_e32 v6, v5, v8, vcc
	v_lshl_add_u64 v[6:7], v[6:7], 0, s[62:63]
	v_lshl_add_u64 v[6:7], v[110:111], 2, v[6:7]
	global_load_dwordx4 v[32:35], v[6:7], off
	s_mov_b32 s16, 0
	v_add3_u32 v2, v9, s16, 0
	s_mov_b32 s0, 0xfffff
	v_mov_b32_e32 v4, 0x24300000
	v_cmp_lt_u32_e32 vcc, s0, v2
	v_mov_b32_e32 v5, 0x28300000
	v_mov_b32_e32 v17, v1
	v_and_b32_e32 v18, 0x3e000, v104
	v_cndmask_b32_e32 v16, v4, v5, vcc
	v_cmp_ne_u32_e64 s[0:1], 0, v18
	v_lshl_add_u64 v[16:17], s[4:5], 0, v[16:17]
	v_lshl_add_u64 v[16:17], v[104:105], 1, v[16:17]
	s_waitcnt vmcnt(3)
	v_cvt_pk_bf16_f32 v12, v20, v21
	v_cvt_pk_bf16_f32 v13, v22, v23
	s_nop 0
	global_store_dwordx2 v[16:17], v[12:13], off
	s_and_saveexec_b64 s[10:11], s[0:1]
	s_cbranch_execz .Lcc_skip_u2_0
	v_mov_b32_e32 v4, 0x6222000
	v_mov_b32_e32 v5, 0xe222000
	v_cndmask_b32_e32 v4, v4, v5, vcc
	v_mov_b32_e32 v5, v1
	v_lshl_add_u64 v[4:5], s[6:7], 0, v[4:5]
	v_lshl_add_u64 v[4:5], v[104:105], 2, v[4:5]
	v_add_co_u32_e32 v4, vcc, 0xffff8000, v4
	s_nop 1
	v_addc_co_u32_e32 v5, vcc, -1, v5, vcc
	s_nop 0
	global_store_dwordx4 v[4:5], v[20:23], off
; __device__ __forceinline__ void cache_convert(const Params& P, int l, int pct0, int pct1, int part, int nparts) {
;     ...
; #pragma unroll 8
;     for (unsigned gi = g0 + (unsigned)part * 512u + tid; gi < g1; gi += (unsigned)nparts * 512u) {
;         const bool isv = gi >= NGL; const unsigned e = (isv ? gi - NGL : gi) * 8u; const int key = (int)((e >> 9) & 511u);
;         const float* src = (isv ? cv : ck) + e;
;         const f32x4 k0 = *(const f32x4*)src, k1 = *(const f32x4*)(src + 4);
;         *(bf16x8*)((isv ? vb : kb) + e) = pack8v(k0, k1);
;         if (key >= 16) { float* d = (isv ? ov : ok) + e - 16 * 512; *(f32x4*)d = k0; *(f32x4*)(d + 4) = k1; }
.Lcc_skip_u2_0:
	s_or_b64 exec, exec, s[10:11]
	v_add3_u32 v2, v9, s16, 32
	s_mov_b32 s0, 0xfffff
	v_mov_b32_e32 v4, 0x24300000
	v_cmp_lt_u32_e32 vcc, s0, v2
	v_mov_b32_e32 v5, 0x28300000
	v_mov_b32_e32 v17, v1
	v_and_b32_e32 v18, 0x3e000, v106
	v_cndmask_b32_e32 v16, v4, v5, vcc
	v_cmp_ne_u32_e64 s[0:1], 0, v18
	v_lshl_add_u64 v[16:17], s[4:5], 0, v[16:17]
	v_lshl_add_u64 v[16:17], v[106:107], 1, v[16:17]
	s_waitcnt vmcnt(3)
	v_cvt_pk_bf16_f32 v14, v24, v25
	v_cvt_pk_bf16_f32 v15, v26, v27
	s_nop 0
	global_store_dwordx2 v[16:17], v[14:15], off
	s_and_saveexec_b64 s[10:11], s[0:1]
	s_cbranch_execz .Lcc_skip_u2_1
	v_mov_b32_e32 v4, 0x6222000
	v_mov_b32_e32 v5, 0xe222000
	v_cndmask_b32_e32 v4, v4, v5, vcc
	v_mov_b32_e32 v5, v1
	v_lshl_add_u64 v[4:5], s[6:7], 0, v[4:5]
	v_lshl_add_u64 v[4:5], v[106:107], 2, v[4:5]
	v_add_co_u32_e32 v4, vcc, 0xffff8000, v4
	s_nop 1
	v_addc_co_u32_e32 v5, vcc, -1, v5, vcc
	s_nop 0
	global_store_dwordx4 v[4:5], v[24:27], off
.Lcc_skip_u2_1:
	s_or_b64 exec, exec, s[10:11]
	s_add_u32 s16, s16, s13
	v_add3_u32 v2, v9, s16, 0
	s_mov_b32 s0, 0xfffff
	v_mov_b32_e32 v4, 0x24300000
	v_cmp_lt_u32_e32 vcc, s0, v2
	v_mov_b32_e32 v5, 0x28300000
	v_mov_b32_e32 v17, v1
	v_and_b32_e32 v18, 0x3e000, v108
	v_cndmask_b32_e32 v16, v4, v5, vcc
	v_cmp_ne_u32_e64 s[0:1], 0, v18
	v_lshl_add_u64 v[16:17], s[4:5], 0, v[16:17]
	v_lshl_add_u64 v[16:17], v[108:109], 1, v[16:17]
	s_waitcnt vmcnt(3)
	v_cvt_pk_bf16_f32 v100, v28, v29
	v_cvt_pk_bf16_f32 v101, v30, v31
	s_nop 0
	global_store_dwordx2 v[16:17], v[100:101], off
	s_and_saveexec_b64 s[10:11], s[0:1]
	s_cbranch_execz .Lcc_skip_u2_2
	v_mov_b32_e32 v4, 0x6222000
	v_mov_b32_e32 v5, 0xe222000
	v_cndmask_b32_e32 v4, v4, v5, vcc
	v_mov_b32_e32 v5, v1
	v_lshl_add_u64 v[4:5], s[6:7], 0, v[4:5]
	v_lshl_add_u64 v[4:5], v[108:109], 2, v[4:5]
	v_add_co_u32_e32 v4, vcc, 0xffff8000, v4
	s_nop 1
	v_addc_co_u32_e32 v5, vcc, -1, v5, vcc
	s_nop 0
	global_store_dwordx4 v[4:5], v[28:31], off
.Lcc_skip_u2_2:
	s_or_b64 exec, exec, s[10:11]
	v_add3_u32 v2, v9, s16, 32
	s_mov_b32 s0, 0xfffff
	v_mov_b32_e32 v4, 0x24300000
	v_cmp_lt_u32_e32 vcc, s0, v2
	v_mov_b32_e32 v5, 0x28300000
	v_mov_b32_e32 v17, v1
	v_and_b32_e32 v18, 0x3e000, v110
	v_cndmask_b32_e32 v16, v4, v5, vcc
	v_cmp_ne_u32_e64 s[0:1], 0, v18
	v_lshl_add_u64 v[16:17], s[4:5], 0, v[16:17]
	v_lshl_add_u64 v[16:17], v[110:111], 1, v[16:17]
	s_waitcnt vmcnt(3)
	v_cvt_pk_bf16_f32 v102, v32, v33
	v_cvt_pk_bf16_f32 v103, v34, v35
	s_nop 0
	global_store_dwordx2 v[16:17], v[102:103], off
	s_and_saveexec_b64 s[10:11], s[0:1]
	s_cbranch_execz .Lcc_skip_u2_3
	v_mov_b32_e32 v4, 0x6222000
	v_mov_b32_e32 v5, 0xe222000
	v_cndmask_b32_e32 v4, v4, v5, vcc
	v_mov_b32_e32 v5, v1
	v_lshl_add_u64 v[4:5], s[6:7], 0, v[4:5]
	v_lshl_add_u64 v[4:5], v[110:111], 2, v[4:5]
	v_add_co_u32_e32 v4, vcc, 0xffff8000, v4
	s_nop 1
	v_addc_co_u32_e32 v5, vcc, -1, v5, vcc
	s_nop 0
	global_store_dwordx4 v[4:5], v[32:35], off
.Lcc_skip_u2_3:
	s_or_b64 exec, exec, s[10:11]
	s_mul_i32 s16, s13, 1
	s_mul_i32 s17, s14, 1
	v_add_u32_e32 v10, s16, v10
	v_add_u32_e32 v11, s17, v11
	s_mov_b64 s[10:11], exec
	s_branch .LBB0_678
